# P3: next unit's Q'/K' chunk prefetched into free VGPRs during stage 4 of the current unit
# baseline (speedup 1.0000x reference)
; #define LAS __attribute__((address_space(3)))
; DI u32x2 pk4(f32x4 v) { u32x2 r; r.x = pk2(v[0], v[1]); r.y = pk2(v[2], v[3]); return r; }
;   const bool dry = mode != 0;
;   unsigned char* ws = p.ws;
;   int tid_ = threadIdx.x; asm volatile("" : "+v"(tid_)); const int tid = tid_, wid = __builtin_amdgcn_readfirstlane(tid >> 6), lane = tid & 63, fr = lane & 15, fq = lane >> 4;
;   const bf16_t* Qr = (const bf16_t*)(ws + OFF_QR); const bf16_t* Kr = (const bf16_t*)(ws + OFF_KR); const bf16_t* Vrt = (const bf16_t*)(ws + OFF_VRT);
;   const bf16_t* RT = (const bf16_t*)p.out;
;   bf16_t* G = (bf16_t*)(ws + OFF_G);
;     ...
;   for (int u = blockIdx.x; u < 1024; u += gridDim.x) {
;     const int bh = u >> 6, c = u & 63, h = bh & 3, b = bh >> 2;
;     const float gam = exp2f(lg2gamma(h));
;     {
;       const u32x4* qg = (const u32x4*)(Qr + (long)(bh * 64 + c) * 16384); const u32x4* kg = (const u32x4*)(Kr + (long)(bh * 64 + c) * 16384);
;       u32x4 qv[4], kv[4];
; #pragma unroll
;       for (int i = 0; i < 4; ++i) { qv[i] = qg[tid + i * NTHREADS]; kv[i] = kg[tid + i * NTHREADS]; }
; #pragma unroll
;       for (int i = 0; i < 4; ++i) { *(LAS u32x4*)(shm + RO_Q + (tid + i * NTHREADS) * 16) = qv[i]; *(LAS u32x4*)(shm + RO_K + (tid + i * NTHREADS) * 16) = kv[i]; }
;     }
;     bf16x8 rf[2][4], vf[2][4];
;     {
;       const bf16_t* rp = RT + (long)(bh * 64 + c) * 32768 + (2 * wid) * 2048 + lane * 8;
;       const bf16_t* vp = Vrt + (long)(bh * 64 + c) * 32768 + (2 * wid) * 2048 + lane * 8;
;     ...
;     {
;       LAS unsigned char* tb = shm + RO_TB + wid * RO_TBW;
; #pragma unroll
;       for (int nt = 0; nt < 8; ++nt) {
;         const f32x2 st = ((const LAS f32x2*)(shm + RO_STAT))[nt * 16 + fr];
; #pragma unroll
;         for (int e2 = 0; e2 < 2; ++e2) *(LAS u32x2*)(tb + (nt * 16 + fr) * 80 + (e2 * 16 + 4 * fq) * 2) = pk4((o[e2][nt] - st.x) * st.y);
;       }
.LBB0_726:
	s_or_b64 exec, exec, s[6:7]
	s_add_u32 s22, s26, 0x2300000
	s_addc_u32 s23, s27, 0
	s_waitcnt vmcnt(27) lgkmcnt(0)
	v_mov_b32_e32 v0, v194
	s_add_u32 s68, s26, 0xc300000
	s_barrier
	s_addc_u32 s69, s27, 0
	s_andn2_b64 vcc, exec, s[0:1]
	v_readfirstlane_b32 s0, v0
	s_cbranch_vccnz .LBB0_755
	s_ashr_i32 s12, s0, 6
	s_lshl_b32 s10, s12, 12
	s_ashr_i32 s11, s10, 31
	s_add_i32 s1, 0, 0x18000
	s_lshl_b64 s[6:7], s[10:11], 1
	s_add_u32 s8, s24, s6
	s_addc_u32 s9, s25, s7
	v_and_b32_e32 v1, 63, v0
	s_waitcnt vmcnt(14)
	v_mov_b32_e32 v91, 0
	s_add_u32 s6, s3, s6
	v_lshlrev_b32_e32 v88, 4, v1
	v_mov_b32_e32 v89, v91
	s_addc_u32 s7, s66, s7
	s_lshl_b32 s3, s12, 4
	s_ashr_i32 s0, s0, 31
	s_waitcnt vmcnt(12)
	v_lshl_add_u64 v[94:95], s[6:7], 0, v[88:89]
	s_or_b32 s6, s3, 15
	s_lshr_b32 s0, s0, 27
	v_and_b32_e32 v3, 15, v0
	s_add_i32 s0, s6, s0
	v_lshl_add_u64 v[92:93], s[8:9], 0, v[88:89]
	s_ashr_i32 s39, s0, 5
	v_or_b32_e32 v89, s3, v3
	s_add_i32 s3, s10, 0
	s_cmpk_gt_i32 s6, 0xffe0
	s_movk_i32 s0, 0x80
	s_cselect_b64 s[40:41], -1, 0
	v_cmp_gt_u32_e64 s[6:7], 16, v1
	v_cmp_gt_i32_e64 s[8:9], s0, v0
	v_lshlrev_b32_e32 v1, 3, v0
	s_add_i32 s11, 0, 0x1a000
	s_mul_i32 s0, s12, 0x2800
	s_waitcnt vmcnt(6)
	v_add_u32_e32 v121, s1, v1
	v_add_u32_e32 v122, s11, v1
	s_add_i32 s13, s0, 0
	v_and_b32_e32 v4, 24, v1
	v_and_b32_e32 v1, 3, v0
	v_lshrrev_b32_e32 v2, 1, v0
	v_lshl_add_u32 v13, v1, 4, s13
	v_lshlrev_b32_e32 v6, 3, v1
	v_ashrrev_i32_e32 v1, 31, v0
	v_lshlrev_b32_e32 v7, 4, v0
	v_and_b32_e32 v9, 24, v2
	v_lshlrev_b32_e32 v2, 8, v0
	v_bfe_u32 v10, v0, 2, 4
	v_lshlrev_b64 v[0:1], 4, v[0:1]
	v_lshlrev_b32_e32 v5, 3, v3
	s_lshl_b32 s30, s12, 10
	v_add_u32_e32 v11, s13, v9
	s_lshl_b32 s0, s12, 5
	v_lshl_add_u64 v[96:97], s[22:23], 0, v[0:1]
	v_lshl_add_u64 v[0:1], s[26:27], 0, v[0:1]
	s_mov_b64 s[12:13], 0x4300000
	v_add_u32_e32 v131, 0, v88
	v_add_u32_e32 v120, s1, v5
	v_add_u32_e32 v123, s11, v5
	v_lshlrev_b32_e32 v8, 10, v10
	v_or_b32_e32 v5, 16, v10
	v_lshl_add_u64 v[98:99], v[0:1], 0, s[12:13]
	v_add_u32_e32 v0, s10, v131
	s_ashr_i32 s1, s0, 31
	v_and_b32_e32 v2, 0x3c00, v2
	v_mul_u32_u24_e32 v15, 0x50, v10
	v_mul_u32_u24_e32 v3, 0x50, v3
	v_mul_u32_u24_e32 v17, 0x50, v5
	v_lshlrev_b32_e32 v10, 10, v5
	v_or_b32_e32 v12, 0x8000, v8
	v_or_b32_e32 v14, 0xc000, v8
	v_or_b32_e32 v16, 0x10000, v8
	v_or_b32_e32 v18, 0x14000, v8
	v_or_b32_e32 v20, 0x18000, v8
	v_or_b32_e32 v22, 0x1c000, v8
	v_add_u32_e32 v132, 0x10000, v0
	v_mbcnt_lo_u32_b32 v0, -1, 0
	s_mov_b32 s18, 0
	s_mov_b32 s19, 0x18000
	s_waitcnt vmcnt(4)
	v_add_u32_e32 v124, 0x80, v123
	v_add_u32_e32 v125, 0x100, v123
	v_add_u32_e32 v126, 0x180, v123
	v_add_u32_e32 v127, 0x200, v123
	v_add_u32_e32 v128, 0x280, v123
	v_add_u32_e32 v129, 0x300, v123
	v_add_u32_e32 v130, 0x380, v123
	s_mov_b32 s31, 0x8000
	s_mov_b32 s38, 0x10000
	s_add_i32 s39, s39, 1
	v_or_b32_e32 v133, 7, v9
	v_add_u32_e32 v134, 0x8000, v131
	v_add_u32_e32 v135, 0, v7
	s_movk_i32 s43, 0x1000
	v_mbcnt_hi_u32_b32 v136, -1, v0
	s_mov_b32 s42, 0x3b800000
	v_add_u32_e32 v137, v11, v3
	s_lshl_b64 s[44:45], s[0:1], 1
	v_lshlrev_b32_e32 v90, 1, v4
	v_lshlrev_b32_e32 v100, 1, v2
	s_mov_b32 s48, 0x20000
	s_mov_b32 s49, 0x28000
	s_mov_b32 s50, 0x30000
	s_mov_b32 s51, 0x38000
	v_lshlrev_b32_e32 v102, 1, v6
	v_add_u32_e32 v138, v13, v15
	v_lshlrev_b32_e32 v104, 1, v8
	v_add_u32_e32 v139, v13, v17
	v_lshlrev_b32_e32 v106, 1, v10
	v_lshlrev_b32_e32 v108, 1, v12
	v_lshlrev_b32_e32 v110, 1, v14
	v_lshlrev_b32_e32 v112, 1, v16
	v_lshlrev_b32_e32 v114, 1, v18
	v_lshlrev_b32_e32 v116, 1, v20
	v_lshlrev_b32_e32 v118, 1, v22
	v_mov_b32_e32 v140, 0x3f7f0000
	v_mov_b32_e32 v141, 0x3f7e0000
	s_mov_b32 s46, s2
	s_mov_b32 s99, 0
	s_mov_b32 s100, 0x2000
	s_mov_b32 s101, 0
	s_branch .LBB0_729
.LBB0_728:
	s_or_b64 exec, exec, s[0:1]
	s_waitcnt lgkmcnt(0)
	s_barrier
	ds_read_b64 v[64:65], v123
	s_ashr_i32 s0, s46, 8
	s_ashr_i32 s1, s0, 31
	s_lshl_b64 s[0:1], s[0:1], 24
	s_add_u32 s0, s68, s0
	s_waitcnt lgkmcnt(0)
	v_sub_f32_e32 v45, v45, v64
	v_sub_f32_e32 v44, v44, v64
	v_sub_f32_e32 v47, v47, v64
	v_sub_f32_e32 v46, v46, v64
	v_sub_f32_e32 v37, v37, v64
	v_sub_f32_e32 v36, v36, v64
	v_sub_f32_e32 v39, v39, v64
	v_sub_f32_e32 v38, v38, v64
	v_pk_mul_f32 v[46:47], v[64:65], v[46:47] op_sel:[1,0]
	v_pk_mul_f32 v[44:45], v[64:65], v[44:45] op_sel:[1,0]
	v_pk_mul_f32 v[38:39], v[64:65], v[38:39] op_sel:[1,0]
	v_pk_mul_f32 v[36:37], v[64:65], v[36:37] op_sel:[1,0]
	v_cvt_pk_bf16_f32 v44, v44, v45
	v_cvt_pk_bf16_f32 v45, v46, v47
	v_cvt_pk_bf16_f32 v36, v36, v37
	v_cvt_pk_bf16_f32 v37, v38, v39
	ds_write2_b64 v137, v[44:45], v[36:37] offset1:4
	ds_read_b64 v[36:37], v124
	s_addc_u32 s1, s69, s1
	s_lshl_b32 s10, s46, 18
	s_and_b32 s10, s10, 0xfc0000
	s_add_u32 s0, s0, s10
	s_waitcnt lgkmcnt(0)
	v_sub_f32_e32 v5, v5, v36
	v_sub_f32_e32 v4, v4, v36
	v_sub_f32_e32 v7, v7, v36
	v_sub_f32_e32 v6, v6, v36
	v_pk_mul_f32 v[6:7], v[36:37], v[6:7] op_sel:[1,0]
	v_pk_mul_f32 v[4:5], v[36:37], v[4:5] op_sel:[1,0]
	s_addc_u32 s1, s1, 0
	v_cvt_pk_bf16_f32 v4, v4, v5
	v_cvt_pk_bf16_f32 v5, v6, v7
	v_sub_f32_e32 v7, v25, v36
	v_sub_f32_e32 v6, v24, v36
	v_sub_f32_e32 v25, v27, v36
	v_sub_f32_e32 v24, v26, v36
	v_pk_mul_f32 v[24:25], v[36:37], v[24:25] op_sel:[1,0]
	v_pk_mul_f32 v[6:7], v[36:37], v[6:7] op_sel:[1,0]
	s_lshl_b32 s10, s52, 9
	v_cvt_pk_bf16_f32 v6, v6, v7
	v_cvt_pk_bf16_f32 v7, v24, v25
	ds_write2_b64 v137, v[4:5], v[6:7] offset0:160 offset1:164
	ds_read_b64 v[4:5], v125
	s_add_u32 s0, s0, s10
	s_addc_u32 s1, s1, 0
	s_add_u32 s0, s0, s44
	s_addc_u32 s1, s1, s45
	s_waitcnt lgkmcnt(0)
; #define LAS __attribute__((address_space(3)))
; DI u32x2 pk4(f32x4 v) { u32x2 r; r.x = pk2(v[0], v[1]); r.y = pk2(v[2], v[3]); return r; }
;     ...
;   for (int u = blockIdx.x; u < 1024; u += gridDim.x) {
;     const int bh = u >> 6, c = u & 63, h = bh & 3, b = bh >> 2;
;     const float gam = exp2f(lg2gamma(h));
;     {
;       const u32x4* qg = (const u32x4*)(Qr + (long)(bh * 64 + c) * 16384); const u32x4* kg = (const u32x4*)(Kr + (long)(bh * 64 + c) * 16384);
;       u32x4 qv[4], kv[4];
; #pragma unroll
;       for (int i = 0; i < 4; ++i) { qv[i] = qg[tid + i * NTHREADS]; kv[i] = kg[tid + i * NTHREADS]; }
;     ...
;     {
;       LAS unsigned char* tb = shm + RO_TB + wid * RO_TBW;
; #pragma unroll
;       for (int nt = 0; nt < 8; ++nt) {
;         const f32x2 st = ((const LAS f32x2*)(shm + RO_STAT))[nt * 16 + fr];
; #pragma unroll
;         for (int e2 = 0; e2 < 2; ++e2) *(LAS u32x2*)(tb + (nt * 16 + fr) * 80 + (e2 * 16 + 4 * fq) * 2) = pk4((o[e2][nt] - st.x) * st.y);
;       }
	v_sub_f32_e32 v7, v9, v4
	v_sub_f32_e32 v6, v8, v4
	v_sub_f32_e32 v9, v11, v4
	v_sub_f32_e32 v8, v10, v4
	v_pk_mul_f32 v[8:9], v[4:5], v[8:9] op_sel:[1,0]
	v_pk_mul_f32 v[6:7], v[4:5], v[6:7] op_sel:[1,0]
	v_sub_f32_e32 v11, v23, v4
	v_cvt_pk_bf16_f32 v6, v6, v7
	v_cvt_pk_bf16_f32 v7, v8, v9
	v_sub_f32_e32 v9, v21, v4
	v_sub_f32_e32 v8, v20, v4
	v_sub_f32_e32 v10, v22, v4
	v_pk_mul_f32 v[10:11], v[4:5], v[10:11] op_sel:[1,0]
	v_pk_mul_f32 v[4:5], v[4:5], v[8:9] op_sel:[1,0]
	v_add_u32_e32 v8, 0x800, v137
	v_cvt_pk_bf16_f32 v4, v4, v5
	v_cvt_pk_bf16_f32 v5, v10, v11
	ds_write2_b64 v8, v[6:7], v[4:5] offset0:64 offset1:68
	ds_read_b64 v[4:5], v126
	v_mov_b32_e32 v101, v91
	v_mov_b32_e32 v103, v91
	v_lshl_add_u64 v[20:21], s[0:1], 0, v[102:103]
	v_mov_b32_e32 v105, v91
	s_waitcnt lgkmcnt(0)
	v_sub_f32_e32 v1, v1, v4
	v_sub_f32_e32 v0, v0, v4
	v_sub_f32_e32 v3, v3, v4
	v_sub_f32_e32 v2, v2, v4
	v_pk_mul_f32 v[2:3], v[4:5], v[2:3] op_sel:[1,0]
	v_pk_mul_f32 v[0:1], v[4:5], v[0:1] op_sel:[1,0]
	v_sub_f32_e32 v7, v19, v4
	v_cvt_pk_bf16_f32 v0, v0, v1
	v_cvt_pk_bf16_f32 v1, v2, v3
	v_sub_f32_e32 v3, v17, v4
	v_sub_f32_e32 v2, v16, v4
	v_sub_f32_e32 v6, v18, v4
	v_pk_mul_f32 v[6:7], v[4:5], v[6:7] op_sel:[1,0]
	v_pk_mul_f32 v[2:3], v[4:5], v[2:3] op_sel:[1,0]
	v_mov_b32_e32 v107, v91
	v_cvt_pk_bf16_f32 v2, v2, v3
	v_cvt_pk_bf16_f32 v3, v6, v7
	ds_write2_b64 v8, v[0:1], v[2:3] offset0:224 offset1:228
	ds_read_b64 v[0:1], v127
	v_add_u32_e32 v8, 0x1800, v137
	v_mov_b32_e32 v109, v91
	v_mov_b32_e32 v111, v91
	v_mov_b32_e32 v113, v91
	s_waitcnt lgkmcnt(0)
	v_sub_f32_e32 v3, v41, v0
	v_sub_f32_e32 v2, v40, v0
	v_sub_f32_e32 v5, v43, v0
	v_sub_f32_e32 v4, v42, v0
	v_pk_mul_f32 v[4:5], v[0:1], v[4:5] op_sel:[1,0]
	v_pk_mul_f32 v[2:3], v[0:1], v[2:3] op_sel:[1,0]
	v_sub_f32_e32 v7, v31, v0
	v_cvt_pk_bf16_f32 v2, v2, v3
	v_cvt_pk_bf16_f32 v3, v4, v5
	v_sub_f32_e32 v5, v29, v0
	v_sub_f32_e32 v4, v28, v0
	v_sub_f32_e32 v6, v30, v0
	v_pk_mul_f32 v[6:7], v[0:1], v[6:7] op_sel:[1,0]
	v_pk_mul_f32 v[0:1], v[0:1], v[4:5] op_sel:[1,0]
	v_add_u32_e32 v4, 0x1000, v137
	v_cvt_pk_bf16_f32 v0, v0, v1
	v_cvt_pk_bf16_f32 v1, v6, v7
	ds_write2_b64 v4, v[2:3], v[0:1] offset0:128 offset1:132
	ds_read_b64 v[0:1], v128
	v_mov_b32_e32 v115, v91
	v_mov_b32_e32 v117, v91
	v_mov_b32_e32 v119, v91
	s_add_i32 s46, s46, s28
	s_cmpk_lt_i32 s46, 0x400
	s_cbranch_scc0 .Lp3pf_skip
	s_ashr_i32 s47, s46, 31
	s_lshl_b64 s[98:99], s[46:47], 15
	v_lshl_add_u64 v[228:229], v[96:97], 0, s[98:99]
	v_lshl_add_u64 v[230:231], v[98:99], 0, s[98:99]
	global_load_dwordx4 v[196:199], v[228:229], off nt
	global_load_dwordx4 v[200:203], v[230:231], off nt
	v_lshl_add_u64 v[228:229], v[228:229], 0, s[100:101]
	v_lshl_add_u64 v[230:231], v[230:231], 0, s[100:101]
	global_load_dwordx4 v[204:207], v[228:229], off nt
	global_load_dwordx4 v[208:211], v[230:231], off nt
	v_lshl_add_u64 v[228:229], v[228:229], 0, s[100:101]
	v_lshl_add_u64 v[230:231], v[230:231], 0, s[100:101]
	global_load_dwordx4 v[212:215], v[228:229], off nt
	global_load_dwordx4 v[216:219], v[230:231], off nt
	v_lshl_add_u64 v[228:229], v[228:229], 0, s[100:101]
	v_lshl_add_u64 v[230:231], v[230:231], 0, s[100:101]
	global_load_dwordx4 v[220:223], v[228:229], off nt
	global_load_dwordx4 v[224:227], v[230:231], off nt
	s_mov_b32 s99, 1
.Lp3pf_skip:
	s_waitcnt lgkmcnt(0)
	v_sub_f32_e32 v3, v13, v0
	v_sub_f32_e32 v2, v12, v0
	v_sub_f32_e32 v5, v15, v0
	v_sub_f32_e32 v4, v14, v0
	v_pk_mul_f32 v[4:5], v[0:1], v[4:5] op_sel:[1,0]
	v_pk_mul_f32 v[2:3], v[0:1], v[2:3] op_sel:[1,0]
	v_sub_f32_e32 v7, v35, v0
	v_cvt_pk_bf16_f32 v2, v2, v3
	v_cvt_pk_bf16_f32 v3, v4, v5
	v_sub_f32_e32 v5, v33, v0
	v_sub_f32_e32 v4, v32, v0
	v_sub_f32_e32 v6, v34, v0
	v_pk_mul_f32 v[6:7], v[0:1], v[6:7] op_sel:[1,0]
	v_pk_mul_f32 v[0:1], v[0:1], v[4:5] op_sel:[1,0]
	s_cmpk_lt_i32 s46, 0x400
	v_cvt_pk_bf16_f32 v0, v0, v1
	v_cvt_pk_bf16_f32 v1, v6, v7
	ds_write2_b64 v8, v[2:3], v[0:1] offset0:32 offset1:36
	ds_read_b64 v[0:1], v129
	s_waitcnt lgkmcnt(0)
	v_sub_f32_e32 v3, v53, v0
	v_sub_f32_e32 v2, v52, v0
	v_sub_f32_e32 v5, v55, v0
	v_sub_f32_e32 v4, v54, v0
	v_pk_mul_f32 v[4:5], v[0:1], v[4:5] op_sel:[1,0]
	v_pk_mul_f32 v[2:3], v[0:1], v[2:3] op_sel:[1,0]
	v_sub_f32_e32 v7, v51, v0
	v_cvt_pk_bf16_f32 v2, v2, v3
	v_cvt_pk_bf16_f32 v3, v4, v5
	v_sub_f32_e32 v5, v49, v0
	v_sub_f32_e32 v4, v48, v0
	v_sub_f32_e32 v6, v50, v0
	v_pk_mul_f32 v[6:7], v[0:1], v[6:7] op_sel:[1,0]
	v_pk_mul_f32 v[0:1], v[0:1], v[4:5] op_sel:[1,0]
	s_nop 0
	v_cvt_pk_bf16_f32 v0, v0, v1
	v_cvt_pk_bf16_f32 v1, v6, v7
	ds_write2_b64 v8, v[2:3], v[0:1] offset0:192 offset1:196
	ds_read_b64 v[0:1], v130
	s_waitcnt lgkmcnt(0)
	v_sub_f32_e32 v3, v61, v0
	v_sub_f32_e32 v2, v60, v0
	v_sub_f32_e32 v5, v63, v0
	v_sub_f32_e32 v4, v62, v0
	v_pk_mul_f32 v[4:5], v[0:1], v[4:5] op_sel:[1,0]
	v_pk_mul_f32 v[2:3], v[0:1], v[2:3] op_sel:[1,0]
	v_sub_f32_e32 v7, v59, v0
	v_cvt_pk_bf16_f32 v2, v2, v3
	v_cvt_pk_bf16_f32 v3, v4, v5
	v_sub_f32_e32 v5, v57, v0
	v_sub_f32_e32 v4, v56, v0
	v_sub_f32_e32 v6, v58, v0
	v_pk_mul_f32 v[6:7], v[0:1], v[6:7] op_sel:[1,0]
	v_pk_mul_f32 v[0:1], v[0:1], v[4:5] op_sel:[1,0]
	v_add_u32_e32 v4, 0x2000, v137
	v_cvt_pk_bf16_f32 v0, v0, v1
	v_cvt_pk_bf16_f32 v1, v6, v7
	ds_write2_b64 v4, v[2:3], v[0:1] offset0:96 offset1:100
	v_lshl_add_u64 v[0:1], s[0:1], 0, v[90:91]
	s_waitcnt lgkmcnt(0)
; #define LAS __attribute__((address_space(3)))
; DI unsigned pk2(float lo, float hi) { f32x2 v = {lo, hi}; bf16v2 b = __builtin_convertvector(v, bf16v2); return __builtin_bit_cast(unsigned, b); }
; DI f32x4 unpk4(u32x2 u) { f32x4 r; r[0] = __uint_as_float(u.x << 16); r[1] = __uint_as_float(u.x & 0xffff0000u); r[2] = __uint_as_float(u.y << 16); r[3] = __uint_as_float(u.y & 0xffff0000u); return r; }
;     ...
;       bf16_t* gbase = G + ((long)b * SEQ + c * 128) * 1024 + h * 256 + 32 * wid;
;       bf16_t* obase = dry ? (bf16_t*)((unsigned char*)p.out + 64 * MiB) + (gbase - G) : gbase;
;       u32x4 gv[8];
; #pragma unroll
;       for (int r = 0; r < 8; ++r) { const int idx = r * 64 + lane; gv[r] = *(const u32x4*)(gbase + (long)(idx >> 2) * 1024 + (idx & 3) * 8); }
; #pragma unroll
;       for (int r = 0; r < 8; ++r) {
;         const int idx = r * 64 + lane, nn = idx >> 2, ch = idx & 3;
;         const u32x4 ov = *(const LAS u32x4*)(tb + nn * 80 + ch * 16);
;         u32x4 w4;
;         { const f32x4 a = unpk4((u32x2){ov.x, ov.y}) * unpk4((u32x2){gv[r].x, gv[r].y}), c2 = unpk4((u32x2){ov.z, ov.w}) * unpk4((u32x2){gv[r].z, gv[r].w});
;           w4.x = pk2(a[0], a[1]); w4.y = pk2(a[2], a[3]); w4.z = pk2(c2[0], c2[1]); w4.w = pk2(c2[2], c2[3]); }
;         *(u32x4*)(obase + (long)nn * 1024 + ch * 8) = w4;
	v_lshl_add_u64 v[0:1], v[0:1], 0, v[100:101]
	global_load_dwordx4 v[22:25], v[0:1], off
	v_add_co_u32_e32 v2, vcc, s31, v0
	s_nop 1
	v_addc_co_u32_e32 v3, vcc, 0, v1, vcc
	global_load_dwordx4 v[26:29], v[2:3], off
	v_add_co_u32_e32 v2, vcc, s38, v0
	s_nop 1
	v_addc_co_u32_e32 v3, vcc, 0, v1, vcc
	v_add_co_u32_e32 v4, vcc, s19, v0
	s_nop 1
	v_addc_co_u32_e32 v5, vcc, 0, v1, vcc
	global_load_dwordx4 v[30:33], v[2:3], off
	global_load_dwordx4 v[16:19], v[4:5], off
	v_add_co_u32_e32 v2, vcc, s48, v0
	s_nop 1
	v_addc_co_u32_e32 v3, vcc, 0, v1, vcc
	v_add_co_u32_e32 v4, vcc, s49, v0
	s_nop 1
	v_addc_co_u32_e32 v5, vcc, 0, v1, vcc
	global_load_dwordx4 v[12:15], v[2:3], off
	global_load_dwordx4 v[8:11], v[4:5], off
	v_add_co_u32_e32 v2, vcc, s50, v0
	ds_read_b128 v[34:37], v138
	s_nop 0
	v_addc_co_u32_e32 v3, vcc, 0, v1, vcc
	v_add_co_u32_e32 v0, vcc, s51, v0
	s_waitcnt lgkmcnt(0)
	v_lshlrev_b32_e32 v42, 16, v34
	v_addc_co_u32_e32 v1, vcc, 0, v1, vcc
	global_load_dwordx4 v[4:7], v[2:3], off
	s_nop 0
	global_load_dwordx4 v[0:3], v[0:1], off
	s_waitcnt vmcnt(7)
	v_lshlrev_b32_e32 v44, 16, v22
	v_and_b32_e32 v45, 0xffff0000, v22
	v_lshlrev_b32_e32 v22, 16, v23
	v_and_b32_e32 v23, 0xffff0000, v23
	ds_read_b128 v[38:41], v139
	v_and_b32_e32 v43, 0xffff0000, v34
	v_lshlrev_b32_e32 v34, 16, v35
	v_and_b32_e32 v35, 0xffff0000, v35
	v_pk_mul_f32 v[34:35], v[22:23], v[34:35]
	v_pk_mul_f32 v[22:23], v[44:45], v[42:43]
	v_lshlrev_b32_e32 v42, 16, v36
	v_and_b32_e32 v43, 0xffff0000, v36
	v_lshlrev_b32_e32 v36, 16, v37
	v_and_b32_e32 v37, 0xffff0000, v37
	v_lshlrev_b32_e32 v44, 16, v24
	v_and_b32_e32 v45, 0xffff0000, v24
	v_lshlrev_b32_e32 v24, 16, v25
	v_and_b32_e32 v25, 0xffff0000, v25
	v_pk_mul_f32 v[36:37], v[24:25], v[36:37]
	v_pk_mul_f32 v[24:25], v[44:45], v[42:43]
	v_cvt_pk_bf16_f32 v22, v22, v23
	v_cvt_pk_bf16_f32 v23, v34, v35
	v_cvt_pk_bf16_f32 v24, v24, v25
	v_cvt_pk_bf16_f32 v25, v36, v37
	v_lshl_add_u64 v[34:35], v[20:21], 0, v[104:105]
	global_store_dwordx4 v[34:35], v[22:25], off
	s_waitcnt vmcnt(7)
	v_lshlrev_b32_e32 v34, 16, v26
	v_and_b32_e32 v35, 0xffff0000, v26
	s_waitcnt lgkmcnt(0)
	v_lshlrev_b32_e32 v22, 16, v38
	v_and_b32_e32 v23, 0xffff0000, v38
	v_lshlrev_b32_e32 v24, 16, v39
	v_and_b32_e32 v25, 0xffff0000, v39
	v_lshlrev_b32_e32 v26, 16, v27
	v_and_b32_e32 v27, 0xffff0000, v27
	v_pk_mul_f32 v[24:25], v[26:27], v[24:25]
	v_pk_mul_f32 v[22:23], v[34:35], v[22:23]
	v_lshlrev_b32_e32 v26, 16, v40
	v_and_b32_e32 v27, 0xffff0000, v40
	v_lshlrev_b32_e32 v34, 16, v41
	v_and_b32_e32 v35, 0xffff0000, v41
	v_lshlrev_b32_e32 v36, 16, v28
	v_and_b32_e32 v37, 0xffff0000, v28
	v_lshlrev_b32_e32 v28, 16, v29
	v_and_b32_e32 v29, 0xffff0000, v29
	v_pk_mul_f32 v[28:29], v[28:29], v[34:35]
	v_pk_mul_f32 v[26:27], v[36:37], v[26:27]
	v_cvt_pk_bf16_f32 v22, v22, v23
	v_cvt_pk_bf16_f32 v23, v24, v25
	v_cvt_pk_bf16_f32 v24, v26, v27
	v_cvt_pk_bf16_f32 v25, v28, v29
	ds_read_b128 v[26:29], v139 offset:1280
	v_lshl_add_u64 v[34:35], v[20:21], 0, v[106:107]
	global_store_dwordx4 v[34:35], v[22:25], off
	ds_read_b128 v[22:25], v139 offset:2560
	s_waitcnt lgkmcnt(1)
	v_lshlrev_b32_e32 v34, 16, v26
	v_and_b32_e32 v35, 0xffff0000, v26
	v_lshlrev_b32_e32 v26, 16, v27
	v_and_b32_e32 v27, 0xffff0000, v27
	s_waitcnt vmcnt(7)
	v_lshlrev_b32_e32 v36, 16, v30
	v_and_b32_e32 v37, 0xffff0000, v30
	v_lshlrev_b32_e32 v30, 16, v31
	v_and_b32_e32 v31, 0xffff0000, v31
	v_pk_mul_f32 v[30:31], v[30:31], v[26:27]
	v_pk_mul_f32 v[26:27], v[36:37], v[34:35]
	v_lshlrev_b32_e32 v34, 16, v28
	v_and_b32_e32 v35, 0xffff0000, v28
	v_lshlrev_b32_e32 v28, 16, v29
	v_and_b32_e32 v29, 0xffff0000, v29
	v_lshlrev_b32_e32 v36, 16, v32
	v_and_b32_e32 v37, 0xffff0000, v32
	v_lshlrev_b32_e32 v32, 16, v33
	v_and_b32_e32 v33, 0xffff0000, v33
	v_pk_mul_f32 v[32:33], v[32:33], v[28:29]
	v_pk_mul_f32 v[28:29], v[36:37], v[34:35]
	v_cvt_pk_bf16_f32 v26, v26, v27
	v_cvt_pk_bf16_f32 v27, v30, v31
	v_cvt_pk_bf16_f32 v28, v28, v29
	v_cvt_pk_bf16_f32 v29, v32, v33
	v_lshl_add_u64 v[30:31], v[20:21], 0, v[108:109]
	global_store_dwordx4 v[30:31], v[26:29], off
	s_waitcnt lgkmcnt(0)
	s_nop 0
	v_lshlrev_b32_e32 v26, 16, v22
	v_and_b32_e32 v27, 0xffff0000, v22
	v_lshlrev_b32_e32 v22, 16, v23
	v_and_b32_e32 v23, 0xffff0000, v23
	s_waitcnt vmcnt(7)
; #define LAS __attribute__((address_space(3)))
; DI unsigned pk2(float lo, float hi) { f32x2 v = {lo, hi}; bf16v2 b = __builtin_convertvector(v, bf16v2); return __builtin_bit_cast(unsigned, b); }
; DI f32x4 unpk4(u32x2 u) { f32x4 r; r[0] = __uint_as_float(u.x << 16); r[1] = __uint_as_float(u.x & 0xffff0000u); r[2] = __uint_as_float(u.y << 16); r[3] = __uint_as_float(u.y & 0xffff0000u); return r; }
;     ...
; #pragma unroll
;       for (int r = 0; r < 8; ++r) {
;         const int idx = r * 64 + lane, nn = idx >> 2, ch = idx & 3;
;         const u32x4 ov = *(const LAS u32x4*)(tb + nn * 80 + ch * 16);
;         u32x4 w4;
;         { const f32x4 a = unpk4((u32x2){ov.x, ov.y}) * unpk4((u32x2){gv[r].x, gv[r].y}), c2 = unpk4((u32x2){ov.z, ov.w}) * unpk4((u32x2){gv[r].z, gv[r].w});
;           w4.x = pk2(a[0], a[1]); w4.y = pk2(a[2], a[3]); w4.z = pk2(c2[0], c2[1]); w4.w = pk2(c2[2], c2[3]); }
;         *(u32x4*)(obase + (long)nn * 1024 + ch * 8) = w4;
;       }
;     }
;     __syncthreads();
	v_lshlrev_b32_e32 v28, 16, v16
	v_and_b32_e32 v29, 0xffff0000, v16
	v_lshlrev_b32_e32 v16, 16, v17
	v_and_b32_e32 v17, 0xffff0000, v17
	v_pk_mul_f32 v[22:23], v[16:17], v[22:23]
	v_pk_mul_f32 v[16:17], v[28:29], v[26:27]
	v_lshlrev_b32_e32 v26, 16, v24
	v_and_b32_e32 v27, 0xffff0000, v24
	v_lshlrev_b32_e32 v24, 16, v25
	v_and_b32_e32 v25, 0xffff0000, v25
	v_lshlrev_b32_e32 v28, 16, v18
	v_and_b32_e32 v29, 0xffff0000, v18
	v_lshlrev_b32_e32 v18, 16, v19
	v_and_b32_e32 v19, 0xffff0000, v19
	v_pk_mul_f32 v[24:25], v[18:19], v[24:25]
	v_pk_mul_f32 v[18:19], v[28:29], v[26:27]
	v_cvt_pk_bf16_f32 v16, v16, v17
	v_cvt_pk_bf16_f32 v17, v22, v23
	v_cvt_pk_bf16_f32 v18, v18, v19
	v_cvt_pk_bf16_f32 v19, v24, v25
	ds_read_b128 v[22:25], v139 offset:3840
	v_lshl_add_u64 v[26:27], v[20:21], 0, v[110:111]
	global_store_dwordx4 v[26:27], v[16:19], off
	ds_read_b128 v[16:19], v139 offset:5120
	s_waitcnt vmcnt(7)
	v_lshlrev_b32_e32 v28, 16, v12
	s_waitcnt lgkmcnt(1)
	v_lshlrev_b32_e32 v26, 16, v22
	v_and_b32_e32 v27, 0xffff0000, v22
	v_lshlrev_b32_e32 v22, 16, v23
	v_and_b32_e32 v23, 0xffff0000, v23
	v_and_b32_e32 v29, 0xffff0000, v12
	v_lshlrev_b32_e32 v12, 16, v13
	v_and_b32_e32 v13, 0xffff0000, v13
	v_pk_mul_f32 v[22:23], v[12:13], v[22:23]
	v_pk_mul_f32 v[12:13], v[28:29], v[26:27]
	v_lshlrev_b32_e32 v26, 16, v24
	v_and_b32_e32 v27, 0xffff0000, v24
	v_lshlrev_b32_e32 v24, 16, v25
	v_and_b32_e32 v25, 0xffff0000, v25
	v_lshlrev_b32_e32 v28, 16, v14
	v_and_b32_e32 v29, 0xffff0000, v14
	v_lshlrev_b32_e32 v14, 16, v15
	v_and_b32_e32 v15, 0xffff0000, v15
	v_pk_mul_f32 v[24:25], v[14:15], v[24:25]
	v_pk_mul_f32 v[14:15], v[28:29], v[26:27]
	v_cvt_pk_bf16_f32 v12, v12, v13
	v_cvt_pk_bf16_f32 v13, v22, v23
	v_cvt_pk_bf16_f32 v14, v14, v15
	v_cvt_pk_bf16_f32 v15, v24, v25
	v_lshl_add_u64 v[22:23], v[20:21], 0, v[112:113]
	global_store_dwordx4 v[22:23], v[12:15], off
	s_waitcnt lgkmcnt(0)
	s_nop 0
	v_lshlrev_b32_e32 v12, 16, v16
	v_and_b32_e32 v13, 0xffff0000, v16
	v_lshlrev_b32_e32 v14, 16, v17
	v_and_b32_e32 v15, 0xffff0000, v17
	s_waitcnt vmcnt(7)
	v_lshlrev_b32_e32 v16, 16, v8
	v_and_b32_e32 v17, 0xffff0000, v8
	v_lshlrev_b32_e32 v8, 16, v9
	v_and_b32_e32 v9, 0xffff0000, v9
	v_pk_mul_f32 v[14:15], v[8:9], v[14:15]
	v_pk_mul_f32 v[8:9], v[16:17], v[12:13]
	v_lshlrev_b32_e32 v12, 16, v18
	v_and_b32_e32 v13, 0xffff0000, v18
	v_lshlrev_b32_e32 v16, 16, v19
	v_and_b32_e32 v17, 0xffff0000, v19
	v_lshlrev_b32_e32 v18, 16, v10
	v_and_b32_e32 v19, 0xffff0000, v10
	v_lshlrev_b32_e32 v10, 16, v11
	v_and_b32_e32 v11, 0xffff0000, v11
	v_pk_mul_f32 v[16:17], v[10:11], v[16:17]
	v_pk_mul_f32 v[10:11], v[18:19], v[12:13]
	v_cvt_pk_bf16_f32 v8, v8, v9
	v_cvt_pk_bf16_f32 v9, v14, v15
	ds_read_b128 v[12:15], v139 offset:6400
	v_cvt_pk_bf16_f32 v10, v10, v11
	v_cvt_pk_bf16_f32 v11, v16, v17
	v_lshl_add_u64 v[16:17], v[20:21], 0, v[114:115]
	global_store_dwordx4 v[16:17], v[8:11], off
	ds_read_b128 v[8:11], v139 offset:7680
	s_waitcnt lgkmcnt(1)
	v_lshlrev_b32_e32 v16, 16, v12
	v_and_b32_e32 v17, 0xffff0000, v12
	v_lshlrev_b32_e32 v12, 16, v13
	v_and_b32_e32 v13, 0xffff0000, v13
	s_waitcnt vmcnt(7)
	v_lshlrev_b32_e32 v18, 16, v4
	v_and_b32_e32 v19, 0xffff0000, v4
	v_lshlrev_b32_e32 v4, 16, v5
	v_and_b32_e32 v5, 0xffff0000, v5
	v_pk_mul_f32 v[12:13], v[4:5], v[12:13]
	v_pk_mul_f32 v[4:5], v[18:19], v[16:17]
	v_lshlrev_b32_e32 v16, 16, v14
	v_and_b32_e32 v17, 0xffff0000, v14
	v_lshlrev_b32_e32 v14, 16, v15
	v_and_b32_e32 v15, 0xffff0000, v15
	v_lshlrev_b32_e32 v18, 16, v6
	v_and_b32_e32 v19, 0xffff0000, v6
	v_lshlrev_b32_e32 v6, 16, v7
	v_and_b32_e32 v7, 0xffff0000, v7
	v_pk_mul_f32 v[14:15], v[6:7], v[14:15]
	v_pk_mul_f32 v[6:7], v[18:19], v[16:17]
	v_cvt_pk_bf16_f32 v4, v4, v5
	v_cvt_pk_bf16_f32 v5, v12, v13
	v_cvt_pk_bf16_f32 v6, v6, v7
	v_cvt_pk_bf16_f32 v7, v14, v15
	v_lshl_add_u64 v[12:13], v[20:21], 0, v[116:117]
	global_store_dwordx4 v[12:13], v[4:7], off
	s_waitcnt lgkmcnt(0)
	s_nop 0
	v_lshlrev_b32_e32 v4, 16, v8
	v_and_b32_e32 v5, 0xffff0000, v8
	v_lshlrev_b32_e32 v6, 16, v9
	v_and_b32_e32 v7, 0xffff0000, v9
	s_waitcnt vmcnt(7)
	v_lshlrev_b32_e32 v8, 16, v0
	v_and_b32_e32 v9, 0xffff0000, v0
	v_lshlrev_b32_e32 v0, 16, v1
	v_and_b32_e32 v1, 0xffff0000, v1
	v_pk_mul_f32 v[6:7], v[0:1], v[6:7]
	v_pk_mul_f32 v[0:1], v[8:9], v[4:5]
	v_lshlrev_b32_e32 v4, 16, v10
	v_and_b32_e32 v5, 0xffff0000, v10
	v_lshlrev_b32_e32 v8, 16, v11
	v_and_b32_e32 v9, 0xffff0000, v11
	v_lshlrev_b32_e32 v10, 16, v2
	v_and_b32_e32 v11, 0xffff0000, v2
	v_lshlrev_b32_e32 v2, 16, v3
	v_and_b32_e32 v3, 0xffff0000, v3
	v_pk_mul_f32 v[8:9], v[2:3], v[8:9]
	v_pk_mul_f32 v[2:3], v[10:11], v[4:5]
	v_cvt_pk_bf16_f32 v0, v0, v1
	v_cvt_pk_bf16_f32 v1, v6, v7
	v_cvt_pk_bf16_f32 v2, v2, v3
	v_cvt_pk_bf16_f32 v3, v8, v9
	v_lshl_add_u64 v[4:5], v[20:21], 0, v[118:119]
	global_store_dwordx4 v[4:5], v[0:3], off
	s_barrier
	s_cbranch_scc0 .LBB0_755

; #define LAS __attribute__((address_space(3)))
;     ...
;       const u32x4* qg = (const u32x4*)(Qr + (long)(bh * 64 + c) * 16384); const u32x4* kg = (const u32x4*)(Kr + (long)(bh * 64 + c) * 16384);
;       u32x4 qv[4], kv[4];
; #pragma unroll
;       for (int i = 0; i < 4; ++i) { qv[i] = qg[tid + i * NTHREADS]; kv[i] = kg[tid + i * NTHREADS]; }
; #pragma unroll
;       for (int i = 0; i < 4; ++i) { *(LAS u32x4*)(shm + RO_Q + (tid + i * NTHREADS) * 16) = qv[i]; *(LAS u32x4*)(shm + RO_K + (tid + i * NTHREADS) * 16) = kv[i]; }
;     }
;     bf16x8 rf[2][4], vf[2][4];
;     {
;       const bf16_t* rp = RT + (long)(bh * 64 + c) * 32768 + (2 * wid) * 2048 + lane * 8;
;       const bf16_t* vp = Vrt + (long)(bh * 64 + c) * 32768 + (2 * wid) * 2048 + lane * 8;
; #pragma unroll
;       for (int e2 = 0; e2 < 2; ++e2)
; #pragma unroll
;         for (int ks = 0; ks < 4; ++ks) { rf[e2][ks] = *(const bf16x8*)(rp + e2 * 2048 + ks * 512); vf[e2][ks] = *(const bf16x8*)(vp + e2 * 2048 + ks * 512); }
;     }
.LBB0_734:
	s_ashr_i32 s47, s46, 31
	s_cmp_eq_u32 s99, 0
	s_cbranch_scc1 .Lp3pf_orig
	s_waitcnt vmcnt(0)
	v_pk_mov_b32 v[32:33], v[196:197], v[196:197] op_sel:[0,1]
	v_pk_mov_b32 v[34:35], v[198:199], v[198:199] op_sel:[0,1]
	v_pk_mov_b32 v[36:37], v[200:201], v[200:201] op_sel:[0,1]
	v_pk_mov_b32 v[38:39], v[202:203], v[202:203] op_sel:[0,1]
	v_pk_mov_b32 v[40:41], v[204:205], v[204:205] op_sel:[0,1]
	v_pk_mov_b32 v[42:43], v[206:207], v[206:207] op_sel:[0,1]
	v_pk_mov_b32 v[44:45], v[208:209], v[208:209] op_sel:[0,1]
	v_pk_mov_b32 v[46:47], v[210:211], v[210:211] op_sel:[0,1]
	v_pk_mov_b32 v[50:51], v[212:213], v[212:213] op_sel:[0,1]
	v_pk_mov_b32 v[52:53], v[214:215], v[214:215] op_sel:[0,1]
	v_pk_mov_b32 v[142:143], v[216:217], v[216:217] op_sel:[0,1]
	v_pk_mov_b32 v[144:145], v[218:219], v[218:219] op_sel:[0,1]
	v_pk_mov_b32 v[146:147], v[220:221], v[220:221] op_sel:[0,1]
	v_pk_mov_b32 v[148:149], v[222:223], v[222:223] op_sel:[0,1]
	v_pk_mov_b32 v[150:151], v[224:225], v[224:225] op_sel:[0,1]
	v_pk_mov_b32 v[152:153], v[226:227], v[226:227] op_sel:[0,1]
	s_lshl_b64 s[0:1], s[46:47], 16
	s_branch .Lp3pf_rv
.Lp3pf_orig:
	s_lshl_b64 s[0:1], s[46:47], 15
	v_lshl_add_u64 v[0:1], v[96:97], 0, s[0:1]
	v_add_co_u32_e32 v4, vcc, 0x2000, v0
	v_lshl_add_u64 v[2:3], v[98:99], 0, s[0:1]
	s_nop 0
	v_addc_co_u32_e32 v5, vcc, 0, v1, vcc
	v_add_co_u32_e32 v6, vcc, 0x2000, v2
	global_load_dwordx4 v[32:35], v[0:1], off nt
	global_load_dwordx4 v[36:39], v[2:3], off nt
	v_addc_co_u32_e32 v7, vcc, 0, v3, vcc
	global_load_dwordx4 v[40:43], v[4:5], off nt
	global_load_dwordx4 v[44:47], v[6:7], off nt
	v_add_co_u32_e32 v4, vcc, 0x4000, v0
	s_lshl_b64 s[0:1], s[46:47], 16
	s_nop 0
	v_addc_co_u32_e32 v5, vcc, 0, v1, vcc
	v_add_co_u32_e32 v6, vcc, 0x4000, v2
	s_nop 1
	v_addc_co_u32_e32 v7, vcc, 0, v3, vcc
	v_add_co_u32_e32 v0, vcc, 0x6000, v0
	global_load_dwordx4 v[50:53], v[4:5], off nt
	global_load_dwordx4 v[142:145], v[6:7], off nt
	v_addc_co_u32_e32 v1, vcc, 0, v1, vcc
	v_add_co_u32_e32 v2, vcc, 0x6000, v2
	s_nop 1
	v_addc_co_u32_e32 v3, vcc, 0, v3, vcc
	global_load_dwordx4 v[146:149], v[0:1], off nt
	global_load_dwordx4 v[150:153], v[2:3], off nt
.Lp3pf_rv:
	v_lshl_add_u64 v[0:1], v[92:93], 0, s[0:1]
	v_lshl_add_u64 v[2:3], v[94:95], 0, s[0:1]
	global_load_dwordx4 v[12:15], v[0:1], off nt
	global_load_dwordx4 v[16:19], v[0:1], off offset:1024 nt
	global_load_dwordx4 v[76:79], v[2:3], off nt
	global_load_dwordx4 v[68:71], v[2:3], off offset:1024 nt
	global_load_dwordx4 v[4:7], v[0:1], off offset:2048 nt
	global_load_dwordx4 v[8:11], v[0:1], off offset:3072 nt
	global_load_dwordx4 v[60:63], v[2:3], off offset:2048 nt
	global_load_dwordx4 v[56:59], v[2:3], off offset:3072 nt
	v_add_co_u32_e32 v0, vcc, s43, v0
	s_nop 1
	v_addc_co_u32_e32 v1, vcc, 0, v1, vcc
	v_add_co_u32_e32 v54, vcc, s43, v2
	s_nop 1
	v_addc_co_u32_e32 v55, vcc, 0, v3, vcc
	global_load_dwordx4 v[24:27], v[0:1], off nt
	global_load_dwordx4 v[28:31], v[0:1], off offset:1024 nt
	global_load_dwordx4 v[84:87], v[54:55], off nt
	global_load_dwordx4 v[80:83], v[54:55], off offset:1024 nt
	global_load_dwordx4 v[20:23], v[0:1], off offset:2048 nt
	s_nop 0
	global_load_dwordx4 v[0:3], v[0:1], off offset:3072 nt
	s_nop 0
	global_load_dwordx4 v[72:75], v[54:55], off offset:2048 nt
	global_load_dwordx4 v[64:67], v[54:55], off offset:3072 nt
	s_andn2_b64 vcc, exec, s[40:41]
	s_waitcnt vmcnt(23)
	ds_write_b128 v135, v[32:35]
	s_waitcnt vmcnt(22)
	ds_write_b128 v135, v[36:39] offset:32768
	s_waitcnt vmcnt(21)
	ds_write_b128 v135, v[40:43] offset:8192
	s_waitcnt vmcnt(20)
	ds_write_b128 v135, v[44:47] offset:40960
	s_waitcnt vmcnt(19)
	ds_write_b128 v135, v[50:53] offset:16384
	s_waitcnt vmcnt(18)
	ds_write_b128 v135, v[142:145] offset:49152
	s_waitcnt vmcnt(17)
	ds_write_b128 v135, v[146:149] offset:24576
	s_waitcnt vmcnt(16)
	ds_write_b128 v135, v[150:153] offset:57344
	s_waitcnt lgkmcnt(0)
	s_barrier
	s_cbranch_vccnz .LBB0_737
	v_add_u32_e32 v44, s3, v88
	ds_read_b128 v[32:35], v44
	ds_read_b128 v[36:39], v44 offset:1024
	ds_read_b128 v[40:43], v44 offset:2048
	ds_read_b128 v[44:47], v44 offset:3072
	v_mov_b32_e32 v49, v134
	v_mov_b32_e32 v50, v133
	v_mov_b32_e32 v51, v132
	s_mov_b32 s47, s39
